# late W_in panels on side CUs, 108 sample-attention units (3 per CU) deferred to P3
# speedup vs baseline: 1.0049x; 1.0049x over previous
; __global__ void __launch_bounds__(NTHR, 2) hybrid_fwd(Args args) {
;     ...
;     if ((int)blockIdx.x >= NAS_FREE_FROM && (int)gridDim.x == 256) {
;         Frame F = make_frame(lds);
;         if (F.tid < 64) { unsigned* fl = (unsigned*)(F.ws + WS_CTL) + CW_QREADY; unsigned sp = 0;
;             while (__hip_atomic_load(fl, __ATOMIC_RELAXED, __HIP_MEMORY_SCOPE_AGENT) < (unsigned)G1_SPECIAL) { __builtin_amdgcn_s_sleep(4); if (++sp > (1u << 22)) break; }
;             __builtin_amdgcn_fence(__ATOMIC_ACQUIRE, "agent"); }
;         asm volatile("s_waitcnt vmcnt(0)" ::: "memory"); __syncthreads();
;         for (int u = (int)blockIdx.x - NAS_FREE_FROM; u < NAS_UNITS; u += 256 - NAS_FREE_FROM) attn_sample_head_unit(F, u);
.LBB0_282:
	s_or_b64 exec, exec, s[6:7]
	s_waitcnt vmcnt(0)
	s_cmpk_gt_i32 s2, 0x2df
	s_waitcnt vmcnt(0) lgkmcnt(0)
	s_barrier
	s_cbranch_scc1 .LBB0_311
	s_ashr_i32 s20, s12, 6
	s_lshl_b32 s6, s20, 2
	s_add_i32 s12, s6, 0
	s_sub_i32 s29, s2, 0xe0
	s_movk_i32 s100, 0x20
	s_movk_i32 s101, 0x174
	s_bitcmp1_b32 s98, 6
	s_cbranch_scc0 .Lattn_p1
	s_add_i32 s29, s2, 0xb8
	s_movk_i32 s100, 36
	s_movk_i32 s101, 0x1dc
